# phase 10 hand-written ff2 GEMM: next-stage LDS-DMA and A-fragment loads interleaved into the MFMA stream
# baseline (speedup 1.0000x reference)
.Lff2a_loop:
	s_waitcnt vmcnt(0)
	s_barrier
	ds_read_b128 v[180:183], v238 offset:0
	ds_read_b128 v[184:187], v238 offset:2048
	ds_read_b128 v[188:191], v238 offset:4096
	ds_read_b128 v[192:195], v238 offset:6144
	ds_read_b128 v[196:199], v238 offset:8192
	ds_read_b128 v[200:203], v238 offset:10240
	ds_read_b128 v[204:207], v238 offset:12288
	ds_read_b128 v[208:211], v238 offset:14336
	ds_read_b128 v[212:215], v238 offset:16384
	ds_read_b128 v[216:219], v238 offset:18432
	ds_read_b128 v[220:223], v238 offset:20480
	ds_read_b128 v[224:227], v238 offset:22528
	s_waitcnt lgkmcnt(11)
	v_mfma_f32_16x16x32_bf16 v[4:7], v[180:183], v[148:151], v[4:7]
	s_add_u32 m0, s50, 0x8000
	v_mfma_f32_16x16x32_bf16 v[68:71], v[180:183], v[156:159], v[68:71]
	global_load_lds_dwordx4 v228, s[46:47]
	ds_read_b128 v[180:183], v238 offset:24576
	s_waitcnt lgkmcnt(11)
	v_mfma_f32_16x16x32_bf16 v[8:11], v[184:187], v[148:151], v[8:11]
	v_mfma_f32_16x16x32_bf16 v[72:75], v[184:187], v[156:159], v[72:75]
	ds_read_b128 v[184:187], v238 offset:26624
	s_waitcnt lgkmcnt(11)
	v_mfma_f32_16x16x32_bf16 v[12:15], v[188:191], v[148:151], v[12:15]
	s_add_u32 m0, s50, 0x9000
	v_mfma_f32_16x16x32_bf16 v[76:79], v[188:191], v[156:159], v[76:79]
	global_load_lds_dwordx4 v229, s[46:47]
	ds_read_b128 v[188:191], v238 offset:28672
	s_waitcnt lgkmcnt(11)
	v_mfma_f32_16x16x32_bf16 v[16:19], v[192:195], v[148:151], v[16:19]
	v_mfma_f32_16x16x32_bf16 v[80:83], v[192:195], v[156:159], v[80:83]
	ds_read_b128 v[192:195], v238 offset:30720
	s_waitcnt lgkmcnt(11)
	v_mfma_f32_16x16x32_bf16 v[20:23], v[196:199], v[148:151], v[20:23]
	s_add_u32 m0, s50, 0xa000
	v_mfma_f32_16x16x32_bf16 v[84:87], v[196:199], v[156:159], v[84:87]
	global_load_lds_dwordx4 v230, s[46:47]
	ds_read_b128 v[196:199], v239 offset:0
	s_waitcnt lgkmcnt(11)
	v_mfma_f32_16x16x32_bf16 v[24:27], v[200:203], v[148:151], v[24:27]
	v_mfma_f32_16x16x32_bf16 v[88:91], v[200:203], v[156:159], v[88:91]
	ds_read_b128 v[200:203], v239 offset:2048
	s_waitcnt lgkmcnt(11)
	v_mfma_f32_16x16x32_bf16 v[28:31], v[204:207], v[148:151], v[28:31]
	s_add_u32 m0, s50, 0xb000
	v_mfma_f32_16x16x32_bf16 v[92:95], v[204:207], v[156:159], v[92:95]
	global_load_lds_dwordx4 v231, s[46:47]
	ds_read_b128 v[204:207], v239 offset:4096
	s_waitcnt lgkmcnt(11)
	v_mfma_f32_16x16x32_bf16 v[32:35], v[208:211], v[148:151], v[32:35]
	v_mfma_f32_16x16x32_bf16 v[96:99], v[208:211], v[156:159], v[96:99]
	ds_read_b128 v[208:211], v239 offset:6144
	s_waitcnt lgkmcnt(11)
	v_mfma_f32_16x16x32_bf16 v[36:39], v[212:215], v[148:151], v[36:39]
	s_add_u32 m0, s50, 0xc000
	v_mfma_f32_16x16x32_bf16 v[100:103], v[212:215], v[156:159], v[100:103]
	global_load_lds_dwordx4 v232, s[46:47]
	ds_read_b128 v[212:215], v239 offset:8192
	s_waitcnt lgkmcnt(11)
	v_mfma_f32_16x16x32_bf16 v[40:43], v[216:219], v[148:151], v[40:43]
	v_mfma_f32_16x16x32_bf16 v[104:107], v[216:219], v[156:159], v[104:107]
	ds_read_b128 v[216:219], v239 offset:10240
	s_waitcnt lgkmcnt(11)
	v_mfma_f32_16x16x32_bf16 v[44:47], v[220:223], v[148:151], v[44:47]
	s_add_u32 m0, s50, 0xd000
	v_mfma_f32_16x16x32_bf16 v[108:111], v[220:223], v[156:159], v[108:111]
	global_load_lds_dwordx4 v233, s[46:47]
	ds_read_b128 v[220:223], v239 offset:12288
	s_waitcnt lgkmcnt(11)
	v_mfma_f32_16x16x32_bf16 v[48:51], v[224:227], v[148:151], v[48:51]
	v_mfma_f32_16x16x32_bf16 v[112:115], v[224:227], v[156:159], v[112:115]
	ds_read_b128 v[224:227], v239 offset:14336
	s_waitcnt lgkmcnt(11)
	v_mfma_f32_16x16x32_bf16 v[52:55], v[180:183], v[148:151], v[52:55]
	s_add_u32 m0, s50, 0xe000
	v_mfma_f32_16x16x32_bf16 v[116:119], v[180:183], v[156:159], v[116:119]
	global_load_lds_dwordx4 v234, s[46:47]
	ds_read_b128 v[180:183], v239 offset:16384
	s_waitcnt lgkmcnt(11)
	v_mfma_f32_16x16x32_bf16 v[56:59], v[184:187], v[148:151], v[56:59]
	v_mfma_f32_16x16x32_bf16 v[120:123], v[184:187], v[156:159], v[120:123]
	ds_read_b128 v[184:187], v239 offset:18432
	s_waitcnt lgkmcnt(11)
	v_mfma_f32_16x16x32_bf16 v[60:63], v[188:191], v[148:151], v[60:63]
	s_add_u32 m0, s50, 0xf000
	v_mfma_f32_16x16x32_bf16 v[124:127], v[188:191], v[156:159], v[124:127]
	global_load_lds_dwordx4 v235, s[46:47]
	ds_read_b128 v[188:191], v239 offset:20480
	s_waitcnt lgkmcnt(11)
	v_mfma_f32_16x16x32_bf16 v[64:67], v[192:195], v[148:151], v[64:67]
	v_mfma_f32_16x16x32_bf16 v[128:131], v[192:195], v[156:159], v[128:131]
	ds_read_b128 v[192:195], v239 offset:22528
	s_waitcnt lgkmcnt(11)
	v_mfma_f32_16x16x32_bf16 v[4:7], v[196:199], v[152:155], v[4:7]
	v_mfma_f32_16x16x32_bf16 v[68:71], v[196:199], v[160:163], v[68:71]
	global_load_dwordx4 v[164:167], v236, s[44:45]
	ds_read_b128 v[196:199], v239 offset:24576
	s_waitcnt lgkmcnt(11)
	v_mfma_f32_16x16x32_bf16 v[8:11], v[200:203], v[152:155], v[8:11]
	v_mfma_f32_16x16x32_bf16 v[72:75], v[200:203], v[160:163], v[72:75]
	ds_read_b128 v[200:203], v239 offset:26624
	s_waitcnt lgkmcnt(11)
	v_mfma_f32_16x16x32_bf16 v[12:15], v[204:207], v[152:155], v[12:15]
	v_mfma_f32_16x16x32_bf16 v[76:79], v[204:207], v[160:163], v[76:79]
	global_load_dwordx4 v[168:171], v236, s[44:45] offset:64
	ds_read_b128 v[204:207], v239 offset:28672
	s_waitcnt lgkmcnt(11)
	v_mfma_f32_16x16x32_bf16 v[16:19], v[208:211], v[152:155], v[16:19]
	v_mfma_f32_16x16x32_bf16 v[80:83], v[208:211], v[160:163], v[80:83]
	ds_read_b128 v[208:211], v239 offset:30720
	s_waitcnt lgkmcnt(11)
	v_mfma_f32_16x16x32_bf16 v[20:23], v[212:215], v[152:155], v[20:23]
	v_mfma_f32_16x16x32_bf16 v[84:87], v[212:215], v[160:163], v[84:87]
	global_load_dwordx4 v[172:175], v237, s[44:45]
	s_waitcnt lgkmcnt(10)
	v_mfma_f32_16x16x32_bf16 v[24:27], v[216:219], v[152:155], v[24:27]
	v_mfma_f32_16x16x32_bf16 v[88:91], v[216:219], v[160:163], v[88:91]
	s_waitcnt lgkmcnt(9)
	v_mfma_f32_16x16x32_bf16 v[28:31], v[220:223], v[152:155], v[28:31]
	v_mfma_f32_16x16x32_bf16 v[92:95], v[220:223], v[160:163], v[92:95]
	global_load_dwordx4 v[176:179], v237, s[44:45] offset:64
	s_waitcnt lgkmcnt(8)
	v_mfma_f32_16x16x32_bf16 v[32:35], v[224:227], v[152:155], v[32:35]
	v_mfma_f32_16x16x32_bf16 v[96:99], v[224:227], v[160:163], v[96:99]
	s_waitcnt lgkmcnt(7)
	v_mfma_f32_16x16x32_bf16 v[36:39], v[180:183], v[152:155], v[36:39]
	v_mfma_f32_16x16x32_bf16 v[100:103], v[180:183], v[160:163], v[100:103]
	s_add_u32 s44, s44, 0x80
	s_addc_u32 s45, s45, 0
	s_add_u32 s46, s46, 0x80
	s_addc_u32 s47, s47, 0
	s_waitcnt lgkmcnt(6)
	v_mfma_f32_16x16x32_bf16 v[40:43], v[184:187], v[152:155], v[40:43]
	v_mfma_f32_16x16x32_bf16 v[104:107], v[184:187], v[160:163], v[104:107]
	s_waitcnt lgkmcnt(5)
	v_mfma_f32_16x16x32_bf16 v[44:47], v[188:191], v[152:155], v[44:47]
	v_mfma_f32_16x16x32_bf16 v[108:111], v[188:191], v[160:163], v[108:111]
	s_waitcnt lgkmcnt(4)
	v_mfma_f32_16x16x32_bf16 v[48:51], v[192:195], v[152:155], v[48:51]
	v_mfma_f32_16x16x32_bf16 v[112:115], v[192:195], v[160:163], v[112:115]
	s_waitcnt lgkmcnt(3)
	v_mfma_f32_16x16x32_bf16 v[52:55], v[196:199], v[152:155], v[52:55]
	v_mfma_f32_16x16x32_bf16 v[116:119], v[196:199], v[160:163], v[116:119]
	s_waitcnt lgkmcnt(2)
	v_mfma_f32_16x16x32_bf16 v[56:59], v[200:203], v[152:155], v[56:59]
	v_mfma_f32_16x16x32_bf16 v[120:123], v[200:203], v[160:163], v[120:123]
	s_waitcnt lgkmcnt(1)
	v_mfma_f32_16x16x32_bf16 v[60:63], v[204:207], v[152:155], v[60:63]
	v_mfma_f32_16x16x32_bf16 v[124:127], v[204:207], v[160:163], v[124:127]
	s_waitcnt lgkmcnt(0)
	v_mfma_f32_16x16x32_bf16 v[64:67], v[208:211], v[152:155], v[64:67]
	v_mfma_f32_16x16x32_bf16 v[128:131], v[208:211], v[160:163], v[128:131]
	s_waitcnt vmcnt(0)
	s_barrier
	s_cmp_eq_u32 s51, 1
	s_cbranch_scc1 .Lff2a_last
	ds_read_b128 v[180:183], v238 offset:32768
	ds_read_b128 v[184:187], v238 offset:34816
	ds_read_b128 v[188:191], v238 offset:36864
	ds_read_b128 v[192:195], v238 offset:38912
	ds_read_b128 v[196:199], v238 offset:40960
	ds_read_b128 v[200:203], v238 offset:43008
	ds_read_b128 v[204:207], v238 offset:45056
	ds_read_b128 v[208:211], v238 offset:47104
	ds_read_b128 v[212:215], v238 offset:49152
	ds_read_b128 v[216:219], v238 offset:51200
	ds_read_b128 v[220:223], v238 offset:53248
	ds_read_b128 v[224:227], v238 offset:55296
	s_waitcnt lgkmcnt(11)
	v_mfma_f32_16x16x32_bf16 v[4:7], v[180:183], v[164:167], v[4:7]
	s_mov_b32 m0, s50
	v_mfma_f32_16x16x32_bf16 v[68:71], v[180:183], v[172:175], v[68:71]
	global_load_lds_dwordx4 v228, s[46:47]
	ds_read_b128 v[180:183], v238 offset:57344
	s_waitcnt lgkmcnt(11)
	v_mfma_f32_16x16x32_bf16 v[8:11], v[184:187], v[164:167], v[8:11]
	v_mfma_f32_16x16x32_bf16 v[72:75], v[184:187], v[172:175], v[72:75]
	ds_read_b128 v[184:187], v238 offset:59392
	s_waitcnt lgkmcnt(11)
	v_mfma_f32_16x16x32_bf16 v[12:15], v[188:191], v[164:167], v[12:15]
	s_add_u32 m0, s50, 0x1000
	v_mfma_f32_16x16x32_bf16 v[76:79], v[188:191], v[172:175], v[76:79]
	global_load_lds_dwordx4 v229, s[46:47]
	ds_read_b128 v[188:191], v238 offset:61440
	s_waitcnt lgkmcnt(11)
	v_mfma_f32_16x16x32_bf16 v[16:19], v[192:195], v[164:167], v[16:19]
	v_mfma_f32_16x16x32_bf16 v[80:83], v[192:195], v[172:175], v[80:83]
	ds_read_b128 v[192:195], v238 offset:63488
	s_waitcnt lgkmcnt(11)
	v_mfma_f32_16x16x32_bf16 v[20:23], v[196:199], v[164:167], v[20:23]
	s_add_u32 m0, s50, 0x2000
	v_mfma_f32_16x16x32_bf16 v[84:87], v[196:199], v[172:175], v[84:87]
	global_load_lds_dwordx4 v230, s[46:47]
	ds_read_b128 v[196:199], v239 offset:32768
	s_waitcnt lgkmcnt(11)
	v_mfma_f32_16x16x32_bf16 v[24:27], v[200:203], v[164:167], v[24:27]
	v_mfma_f32_16x16x32_bf16 v[88:91], v[200:203], v[172:175], v[88:91]
	ds_read_b128 v[200:203], v239 offset:34816
	s_waitcnt lgkmcnt(11)
	v_mfma_f32_16x16x32_bf16 v[28:31], v[204:207], v[164:167], v[28:31]
	s_add_u32 m0, s50, 0x3000
	v_mfma_f32_16x16x32_bf16 v[92:95], v[204:207], v[172:175], v[92:95]
	global_load_lds_dwordx4 v231, s[46:47]
	ds_read_b128 v[204:207], v239 offset:36864
	s_waitcnt lgkmcnt(11)
	v_mfma_f32_16x16x32_bf16 v[32:35], v[208:211], v[164:167], v[32:35]
	v_mfma_f32_16x16x32_bf16 v[96:99], v[208:211], v[172:175], v[96:99]
	ds_read_b128 v[208:211], v239 offset:38912
	s_waitcnt lgkmcnt(11)
	v_mfma_f32_16x16x32_bf16 v[36:39], v[212:215], v[164:167], v[36:39]
	s_add_u32 m0, s50, 0x4000
	v_mfma_f32_16x16x32_bf16 v[100:103], v[212:215], v[172:175], v[100:103]
	global_load_lds_dwordx4 v232, s[46:47]
	ds_read_b128 v[212:215], v239 offset:40960
	s_waitcnt lgkmcnt(11)
	v_mfma_f32_16x16x32_bf16 v[40:43], v[216:219], v[164:167], v[40:43]
	v_mfma_f32_16x16x32_bf16 v[104:107], v[216:219], v[172:175], v[104:107]
	ds_read_b128 v[216:219], v239 offset:43008
	s_waitcnt lgkmcnt(11)
	v_mfma_f32_16x16x32_bf16 v[44:47], v[220:223], v[164:167], v[44:47]
	s_add_u32 m0, s50, 0x5000
	v_mfma_f32_16x16x32_bf16 v[108:111], v[220:223], v[172:175], v[108:111]
	global_load_lds_dwordx4 v233, s[46:47]
	ds_read_b128 v[220:223], v239 offset:45056
	s_waitcnt lgkmcnt(11)
	v_mfma_f32_16x16x32_bf16 v[48:51], v[224:227], v[164:167], v[48:51]
	v_mfma_f32_16x16x32_bf16 v[112:115], v[224:227], v[172:175], v[112:115]
	ds_read_b128 v[224:227], v239 offset:47104
	s_waitcnt lgkmcnt(11)
	v_mfma_f32_16x16x32_bf16 v[52:55], v[180:183], v[164:167], v[52:55]
	s_add_u32 m0, s50, 0x6000
	v_mfma_f32_16x16x32_bf16 v[116:119], v[180:183], v[172:175], v[116:119]
	global_load_lds_dwordx4 v234, s[46:47]
	ds_read_b128 v[180:183], v239 offset:49152
	s_waitcnt lgkmcnt(11)
	v_mfma_f32_16x16x32_bf16 v[56:59], v[184:187], v[164:167], v[56:59]
	v_mfma_f32_16x16x32_bf16 v[120:123], v[184:187], v[172:175], v[120:123]
	ds_read_b128 v[184:187], v239 offset:51200
	s_waitcnt lgkmcnt(11)
	v_mfma_f32_16x16x32_bf16 v[60:63], v[188:191], v[164:167], v[60:63]
	s_add_u32 m0, s50, 0x7000
	v_mfma_f32_16x16x32_bf16 v[124:127], v[188:191], v[172:175], v[124:127]
	global_load_lds_dwordx4 v235, s[46:47]
	ds_read_b128 v[188:191], v239 offset:53248
	s_waitcnt lgkmcnt(11)
	v_mfma_f32_16x16x32_bf16 v[64:67], v[192:195], v[164:167], v[64:67]
	v_mfma_f32_16x16x32_bf16 v[128:131], v[192:195], v[172:175], v[128:131]
	ds_read_b128 v[192:195], v239 offset:55296
	s_waitcnt lgkmcnt(11)
	v_mfma_f32_16x16x32_bf16 v[4:7], v[196:199], v[168:171], v[4:7]
	v_mfma_f32_16x16x32_bf16 v[68:71], v[196:199], v[176:179], v[68:71]
	global_load_dwordx4 v[148:151], v236, s[44:45]
	ds_read_b128 v[196:199], v239 offset:57344
	s_waitcnt lgkmcnt(11)
	v_mfma_f32_16x16x32_bf16 v[8:11], v[200:203], v[168:171], v[8:11]
	v_mfma_f32_16x16x32_bf16 v[72:75], v[200:203], v[176:179], v[72:75]
	ds_read_b128 v[200:203], v239 offset:59392
	s_waitcnt lgkmcnt(11)
	v_mfma_f32_16x16x32_bf16 v[12:15], v[204:207], v[168:171], v[12:15]
	v_mfma_f32_16x16x32_bf16 v[76:79], v[204:207], v[176:179], v[76:79]
	global_load_dwordx4 v[152:155], v236, s[44:45] offset:64
	ds_read_b128 v[204:207], v239 offset:61440
	s_waitcnt lgkmcnt(11)
	v_mfma_f32_16x16x32_bf16 v[16:19], v[208:211], v[168:171], v[16:19]
	v_mfma_f32_16x16x32_bf16 v[80:83], v[208:211], v[176:179], v[80:83]
	ds_read_b128 v[208:211], v239 offset:63488
	s_waitcnt lgkmcnt(11)
	v_mfma_f32_16x16x32_bf16 v[20:23], v[212:215], v[168:171], v[20:23]
	v_mfma_f32_16x16x32_bf16 v[84:87], v[212:215], v[176:179], v[84:87]
	global_load_dwordx4 v[156:159], v237, s[44:45]
	s_waitcnt lgkmcnt(10)
	v_mfma_f32_16x16x32_bf16 v[24:27], v[216:219], v[168:171], v[24:27]
	v_mfma_f32_16x16x32_bf16 v[88:91], v[216:219], v[176:179], v[88:91]
	s_waitcnt lgkmcnt(9)
	v_mfma_f32_16x16x32_bf16 v[28:31], v[220:223], v[168:171], v[28:31]
	v_mfma_f32_16x16x32_bf16 v[92:95], v[220:223], v[176:179], v[92:95]
	global_load_dwordx4 v[160:163], v237, s[44:45] offset:64
	s_waitcnt lgkmcnt(8)
	v_mfma_f32_16x16x32_bf16 v[32:35], v[224:227], v[168:171], v[32:35]
	v_mfma_f32_16x16x32_bf16 v[96:99], v[224:227], v[176:179], v[96:99]
	s_waitcnt lgkmcnt(7)
	v_mfma_f32_16x16x32_bf16 v[36:39], v[180:183], v[168:171], v[36:39]
	v_mfma_f32_16x16x32_bf16 v[100:103], v[180:183], v[176:179], v[100:103]
	s_add_u32 s44, s44, 0x80
	s_addc_u32 s45, s45, 0
	s_add_u32 s46, s46, 0x80
	s_addc_u32 s47, s47, 0
	s_waitcnt lgkmcnt(6)
	v_mfma_f32_16x16x32_bf16 v[40:43], v[184:187], v[168:171], v[40:43]
	v_mfma_f32_16x16x32_bf16 v[104:107], v[184:187], v[176:179], v[104:107]
	s_waitcnt lgkmcnt(5)
	v_mfma_f32_16x16x32_bf16 v[44:47], v[188:191], v[168:171], v[44:47]
	v_mfma_f32_16x16x32_bf16 v[108:111], v[188:191], v[176:179], v[108:111]
	s_waitcnt lgkmcnt(4)
	v_mfma_f32_16x16x32_bf16 v[48:51], v[192:195], v[168:171], v[48:51]
	v_mfma_f32_16x16x32_bf16 v[112:115], v[192:195], v[176:179], v[112:115]
	s_waitcnt lgkmcnt(3)
	v_mfma_f32_16x16x32_bf16 v[52:55], v[196:199], v[168:171], v[52:55]
	v_mfma_f32_16x16x32_bf16 v[116:119], v[196:199], v[176:179], v[116:119]
	s_waitcnt lgkmcnt(2)
	v_mfma_f32_16x16x32_bf16 v[56:59], v[200:203], v[168:171], v[56:59]
	v_mfma_f32_16x16x32_bf16 v[120:123], v[200:203], v[176:179], v[120:123]
	s_waitcnt lgkmcnt(1)
	v_mfma_f32_16x16x32_bf16 v[60:63], v[204:207], v[168:171], v[60:63]
	v_mfma_f32_16x16x32_bf16 v[124:127], v[204:207], v[176:179], v[124:127]
	s_waitcnt lgkmcnt(0)
	v_mfma_f32_16x16x32_bf16 v[64:67], v[208:211], v[168:171], v[64:67]
	v_mfma_f32_16x16x32_bf16 v[128:131], v[208:211], v[176:179], v[128:131]
	s_branch .Lff2a_last_join
.Lff2a_last:
	ds_read_b128 v[180:183], v238 offset:32768
	ds_read_b128 v[184:187], v238 offset:34816
	ds_read_b128 v[188:191], v238 offset:36864
	ds_read_b128 v[192:195], v238 offset:38912
	ds_read_b128 v[196:199], v238 offset:40960
	ds_read_b128 v[200:203], v238 offset:43008
	ds_read_b128 v[204:207], v238 offset:45056
	ds_read_b128 v[208:211], v238 offset:47104
	ds_read_b128 v[212:215], v238 offset:49152
	ds_read_b128 v[216:219], v238 offset:51200
	ds_read_b128 v[220:223], v238 offset:53248
	ds_read_b128 v[224:227], v238 offset:55296
	s_waitcnt lgkmcnt(11)
	v_mfma_f32_16x16x32_bf16 v[4:7], v[180:183], v[164:167], v[4:7]
	v_mfma_f32_16x16x32_bf16 v[68:71], v[180:183], v[172:175], v[68:71]
	ds_read_b128 v[180:183], v238 offset:57344
	s_waitcnt lgkmcnt(11)
	v_mfma_f32_16x16x32_bf16 v[8:11], v[184:187], v[164:167], v[8:11]
	v_mfma_f32_16x16x32_bf16 v[72:75], v[184:187], v[172:175], v[72:75]
	ds_read_b128 v[184:187], v238 offset:59392
	s_waitcnt lgkmcnt(11)
	v_mfma_f32_16x16x32_bf16 v[12:15], v[188:191], v[164:167], v[12:15]
	v_mfma_f32_16x16x32_bf16 v[76:79], v[188:191], v[172:175], v[76:79]
	ds_read_b128 v[188:191], v238 offset:61440
	s_waitcnt lgkmcnt(11)
	v_mfma_f32_16x16x32_bf16 v[16:19], v[192:195], v[164:167], v[16:19]
	v_mfma_f32_16x16x32_bf16 v[80:83], v[192:195], v[172:175], v[80:83]
	ds_read_b128 v[192:195], v238 offset:63488
	s_waitcnt lgkmcnt(11)
	v_mfma_f32_16x16x32_bf16 v[20:23], v[196:199], v[164:167], v[20:23]
	v_mfma_f32_16x16x32_bf16 v[84:87], v[196:199], v[172:175], v[84:87]
	ds_read_b128 v[196:199], v239 offset:32768
	s_waitcnt lgkmcnt(11)
	v_mfma_f32_16x16x32_bf16 v[24:27], v[200:203], v[164:167], v[24:27]
	v_mfma_f32_16x16x32_bf16 v[88:91], v[200:203], v[172:175], v[88:91]
	ds_read_b128 v[200:203], v239 offset:34816
	s_waitcnt lgkmcnt(11)
	v_mfma_f32_16x16x32_bf16 v[28:31], v[204:207], v[164:167], v[28:31]
	v_mfma_f32_16x16x32_bf16 v[92:95], v[204:207], v[172:175], v[92:95]
	ds_read_b128 v[204:207], v239 offset:36864
	s_waitcnt lgkmcnt(11)
	v_mfma_f32_16x16x32_bf16 v[32:35], v[208:211], v[164:167], v[32:35]
	v_mfma_f32_16x16x32_bf16 v[96:99], v[208:211], v[172:175], v[96:99]
	ds_read_b128 v[208:211], v239 offset:38912
	s_waitcnt lgkmcnt(11)
	v_mfma_f32_16x16x32_bf16 v[36:39], v[212:215], v[164:167], v[36:39]
	v_mfma_f32_16x16x32_bf16 v[100:103], v[212:215], v[172:175], v[100:103]
	ds_read_b128 v[212:215], v239 offset:40960
	s_waitcnt lgkmcnt(11)
	v_mfma_f32_16x16x32_bf16 v[40:43], v[216:219], v[164:167], v[40:43]
	v_mfma_f32_16x16x32_bf16 v[104:107], v[216:219], v[172:175], v[104:107]
	ds_read_b128 v[216:219], v239 offset:43008
	s_waitcnt lgkmcnt(11)
	v_mfma_f32_16x16x32_bf16 v[44:47], v[220:223], v[164:167], v[44:47]
	v_mfma_f32_16x16x32_bf16 v[108:111], v[220:223], v[172:175], v[108:111]
	ds_read_b128 v[220:223], v239 offset:45056
	s_waitcnt lgkmcnt(11)
	v_mfma_f32_16x16x32_bf16 v[48:51], v[224:227], v[164:167], v[48:51]
	v_mfma_f32_16x16x32_bf16 v[112:115], v[224:227], v[172:175], v[112:115]
	ds_read_b128 v[224:227], v239 offset:47104
	s_waitcnt lgkmcnt(11)
	v_mfma_f32_16x16x32_bf16 v[52:55], v[180:183], v[164:167], v[52:55]
	v_mfma_f32_16x16x32_bf16 v[116:119], v[180:183], v[172:175], v[116:119]
	ds_read_b128 v[180:183], v239 offset:49152
	s_waitcnt lgkmcnt(11)
	v_mfma_f32_16x16x32_bf16 v[56:59], v[184:187], v[164:167], v[56:59]
	v_mfma_f32_16x16x32_bf16 v[120:123], v[184:187], v[172:175], v[120:123]
	ds_read_b128 v[184:187], v239 offset:51200
	s_waitcnt lgkmcnt(11)
	v_mfma_f32_16x16x32_bf16 v[60:63], v[188:191], v[164:167], v[60:63]
	v_mfma_f32_16x16x32_bf16 v[124:127], v[188:191], v[172:175], v[124:127]
	ds_read_b128 v[188:191], v239 offset:53248
	s_waitcnt lgkmcnt(11)
	v_mfma_f32_16x16x32_bf16 v[64:67], v[192:195], v[164:167], v[64:67]
	v_mfma_f32_16x16x32_bf16 v[128:131], v[192:195], v[172:175], v[128:131]
	ds_read_b128 v[192:195], v239 offset:55296
	s_waitcnt lgkmcnt(11)
	v_mfma_f32_16x16x32_bf16 v[4:7], v[196:199], v[168:171], v[4:7]
	v_mfma_f32_16x16x32_bf16 v[68:71], v[196:199], v[176:179], v[68:71]
	ds_read_b128 v[196:199], v239 offset:57344
	s_waitcnt lgkmcnt(11)
	v_mfma_f32_16x16x32_bf16 v[8:11], v[200:203], v[168:171], v[8:11]
	v_mfma_f32_16x16x32_bf16 v[72:75], v[200:203], v[176:179], v[72:75]
	ds_read_b128 v[200:203], v239 offset:59392
	s_waitcnt lgkmcnt(11)
	v_mfma_f32_16x16x32_bf16 v[12:15], v[204:207], v[168:171], v[12:15]
	v_mfma_f32_16x16x32_bf16 v[76:79], v[204:207], v[176:179], v[76:79]
	ds_read_b128 v[204:207], v239 offset:61440
	s_waitcnt lgkmcnt(11)
	v_mfma_f32_16x16x32_bf16 v[16:19], v[208:211], v[168:171], v[16:19]
	v_mfma_f32_16x16x32_bf16 v[80:83], v[208:211], v[176:179], v[80:83]
	ds_read_b128 v[208:211], v239 offset:63488
	s_waitcnt lgkmcnt(11)
	v_mfma_f32_16x16x32_bf16 v[20:23], v[212:215], v[168:171], v[20:23]
	v_mfma_f32_16x16x32_bf16 v[84:87], v[212:215], v[176:179], v[84:87]
	s_waitcnt lgkmcnt(10)
	v_mfma_f32_16x16x32_bf16 v[24:27], v[216:219], v[168:171], v[24:27]
	v_mfma_f32_16x16x32_bf16 v[88:91], v[216:219], v[176:179], v[88:91]
	s_waitcnt lgkmcnt(9)
	v_mfma_f32_16x16x32_bf16 v[28:31], v[220:223], v[168:171], v[28:31]
	v_mfma_f32_16x16x32_bf16 v[92:95], v[220:223], v[176:179], v[92:95]
	s_waitcnt lgkmcnt(8)
	v_mfma_f32_16x16x32_bf16 v[32:35], v[224:227], v[168:171], v[32:35]
	v_mfma_f32_16x16x32_bf16 v[96:99], v[224:227], v[176:179], v[96:99]
	s_waitcnt lgkmcnt(7)
	v_mfma_f32_16x16x32_bf16 v[36:39], v[180:183], v[168:171], v[36:39]
	v_mfma_f32_16x16x32_bf16 v[100:103], v[180:183], v[176:179], v[100:103]
	s_waitcnt lgkmcnt(6)
	v_mfma_f32_16x16x32_bf16 v[40:43], v[184:187], v[168:171], v[40:43]
	v_mfma_f32_16x16x32_bf16 v[104:107], v[184:187], v[176:179], v[104:107]
	s_waitcnt lgkmcnt(5)
	v_mfma_f32_16x16x32_bf16 v[44:47], v[188:191], v[168:171], v[44:47]
	v_mfma_f32_16x16x32_bf16 v[108:111], v[188:191], v[176:179], v[108:111]
	s_waitcnt lgkmcnt(4)
	v_mfma_f32_16x16x32_bf16 v[48:51], v[192:195], v[168:171], v[48:51]
	v_mfma_f32_16x16x32_bf16 v[112:115], v[192:195], v[176:179], v[112:115]
	s_waitcnt lgkmcnt(3)
	v_mfma_f32_16x16x32_bf16 v[52:55], v[196:199], v[168:171], v[52:55]
	v_mfma_f32_16x16x32_bf16 v[116:119], v[196:199], v[176:179], v[116:119]
	s_waitcnt lgkmcnt(2)
	v_mfma_f32_16x16x32_bf16 v[56:59], v[200:203], v[168:171], v[56:59]
	v_mfma_f32_16x16x32_bf16 v[120:123], v[200:203], v[176:179], v[120:123]
	s_waitcnt lgkmcnt(1)
	v_mfma_f32_16x16x32_bf16 v[60:63], v[204:207], v[168:171], v[60:63]
	v_mfma_f32_16x16x32_bf16 v[124:127], v[204:207], v[176:179], v[124:127]
	s_waitcnt lgkmcnt(0)
	v_mfma_f32_16x16x32_bf16 v[64:67], v[208:211], v[168:171], v[64:67]
	v_mfma_f32_16x16x32_bf16 v[128:131], v[208:211], v[176:179], v[128:131]
.Lff2a_last_join:
	s_sub_u32 s51, s51, 1
	s_cmp_lg_u32 s51, 0
	s_cbranch_scc1 .Lff2a_loop
	s_nop 7
	v_lshlrev_b32_e32 v246, 4, v135
	v_lshl_add_u32 v244, v134, 12, v246
	v_add_u32_e32 v245, 0x10000, v244
	global_load_dwordx4 v[148:151], v246, s[54:55]
	global_load_dwordx4 v[152:155], v246, s[54:55] offset:64
	global_load_dwordx4 v[156:159], v246, s[54:55] offset:128
	global_load_dwordx4 v[160:163], v246, s[54:55] offset:192
	global_load_dwordx4 v[164:167], v246, s[54:55] offset:256
	global_load_dwordx4 v[168:171], v246, s[54:55] offset:320
	global_load_dwordx4 v[172:175], v246, s[54:55] offset:384
	global_load_dwordx4 v[176:179], v246, s[54:55] offset:448
	global_load_dwordx4 v[180:183], v246, s[54:55] offset:512
	global_load_dwordx4 v[184:187], v246, s[54:55] offset:576
	global_load_dwordx4 v[188:191], v246, s[54:55] offset:640
	global_load_dwordx4 v[192:195], v246, s[54:55] offset:704
	global_load_dwordx4 v[196:199], v246, s[54:55] offset:768
	global_load_dwordx4 v[200:203], v246, s[54:55] offset:832
	global_load_dwordx4 v[204:207], v246, s[54:55] offset:896
	global_load_dwordx4 v[208:211], v246, s[54:55] offset:960
	global_load_dwordx4 v[212:215], v244, s[52:53]
	global_load_dwordx4 v[216:219], v244, s[52:53] offset:64
	global_load_dwordx4 v[220:223], v244, s[52:53] offset:128
	global_load_dwordx4 v[224:227], v244, s[52:53] offset:192
	global_load_dwordx4 v[228:231], v244, s[52:53] offset:256
	global_load_dwordx4 v[232:235], v244, s[52:53] offset:320
	global_load_dwordx4 v[236:239], v244, s[52:53] offset:384
	global_load_dwordx4 v[240:243], v244, s[52:53] offset:448
	s_waitcnt vmcnt(4)
	v_fmac_f32_e32 v212, v148, v4
	v_fmac_f32_e32 v213, v149, v5
	v_fmac_f32_e32 v214, v150, v6
	v_fmac_f32_e32 v215, v151, v7
	v_fmac_f32_e32 v216, v152, v8
	v_fmac_f32_e32 v217, v153, v9
	v_fmac_f32_e32 v218, v154, v10
	v_fmac_f32_e32 v219, v155, v11
	v_fmac_f32_e32 v220, v156, v12
	v_fmac_f32_e32 v221, v157, v13
	v_fmac_f32_e32 v222, v158, v14
	v_fmac_f32_e32 v223, v159, v15
	v_fmac_f32_e32 v224, v160, v16
	v_fmac_f32_e32 v225, v161, v17
	v_fmac_f32_e32 v226, v162, v18
	v_fmac_f32_e32 v227, v163, v19
	global_store_dwordx4 v244, v[212:215], s[52:53]
	global_store_dwordx4 v244, v[216:219], s[52:53] offset:64
	global_store_dwordx4 v244, v[220:223], s[52:53] offset:128
	global_store_dwordx4 v244, v[224:227], s[52:53] offset:192
	global_load_dwordx4 v[212:215], v244, s[52:53] offset:512
	global_load_dwordx4 v[216:219], v244, s[52:53] offset:576
	global_load_dwordx4 v[220:223], v244, s[52:53] offset:640
	global_load_dwordx4 v[224:227], v244, s[52:53] offset:704
	s_waitcnt vmcnt(4)
	v_fmac_f32_e32 v228, v164, v20
	v_fmac_f32_e32 v229, v165, v21
	v_fmac_f32_e32 v230, v166, v22
	v_fmac_f32_e32 v231, v167, v23
	v_fmac_f32_e32 v232, v168, v24
	v_fmac_f32_e32 v233, v169, v25
	v_fmac_f32_e32 v234, v170, v26
	v_fmac_f32_e32 v235, v171, v27
	v_fmac_f32_e32 v236, v172, v28
	v_fmac_f32_e32 v237, v173, v29
	v_fmac_f32_e32 v238, v174, v30
	v_fmac_f32_e32 v239, v175, v31
	v_fmac_f32_e32 v240, v176, v32
	v_fmac_f32_e32 v241, v177, v33
	v_fmac_f32_e32 v242, v178, v34
	v_fmac_f32_e32 v243, v179, v35
	global_store_dwordx4 v244, v[228:231], s[52:53] offset:256
	global_store_dwordx4 v244, v[232:235], s[52:53] offset:320
	global_store_dwordx4 v244, v[236:239], s[52:53] offset:384
	global_store_dwordx4 v244, v[240:243], s[52:53] offset:448
	global_load_dwordx4 v[228:231], v244, s[52:53] offset:768
	global_load_dwordx4 v[232:235], v244, s[52:53] offset:832
	global_load_dwordx4 v[236:239], v244, s[52:53] offset:896
	global_load_dwordx4 v[240:243], v244, s[52:53] offset:960
	s_waitcnt vmcnt(4)
	v_fmac_f32_e32 v212, v180, v36
	v_fmac_f32_e32 v213, v181, v37
	v_fmac_f32_e32 v214, v182, v38
	v_fmac_f32_e32 v215, v183, v39
	v_fmac_f32_e32 v216, v184, v40
	v_fmac_f32_e32 v217, v185, v41
	v_fmac_f32_e32 v218, v186, v42
	v_fmac_f32_e32 v219, v187, v43
	v_fmac_f32_e32 v220, v188, v44
	v_fmac_f32_e32 v221, v189, v45
	v_fmac_f32_e32 v222, v190, v46
	v_fmac_f32_e32 v223, v191, v47
	v_fmac_f32_e32 v224, v192, v48
	v_fmac_f32_e32 v225, v193, v49
	v_fmac_f32_e32 v226, v194, v50
	v_fmac_f32_e32 v227, v195, v51
	global_store_dwordx4 v244, v[212:215], s[52:53] offset:512
	global_store_dwordx4 v244, v[216:219], s[52:53] offset:576
	global_store_dwordx4 v244, v[220:223], s[52:53] offset:640
	global_store_dwordx4 v244, v[224:227], s[52:53] offset:704
	global_load_dwordx4 v[212:215], v245, s[52:53]
	global_load_dwordx4 v[216:219], v245, s[52:53] offset:64
	global_load_dwordx4 v[220:223], v245, s[52:53] offset:128
	global_load_dwordx4 v[224:227], v245, s[52:53] offset:192
	s_waitcnt vmcnt(4)
	v_fmac_f32_e32 v228, v196, v52
	v_fmac_f32_e32 v229, v197, v53
	v_fmac_f32_e32 v230, v198, v54
	v_fmac_f32_e32 v231, v199, v55
	v_fmac_f32_e32 v232, v200, v56
	v_fmac_f32_e32 v233, v201, v57
	v_fmac_f32_e32 v234, v202, v58
	v_fmac_f32_e32 v235, v203, v59
	v_fmac_f32_e32 v236, v204, v60
	v_fmac_f32_e32 v237, v205, v61
	v_fmac_f32_e32 v238, v206, v62
	v_fmac_f32_e32 v239, v207, v63
	v_fmac_f32_e32 v240, v208, v64
	v_fmac_f32_e32 v241, v209, v65
	v_fmac_f32_e32 v242, v210, v66
	v_fmac_f32_e32 v243, v211, v67
	global_store_dwordx4 v244, v[228:231], s[52:53] offset:768
	global_store_dwordx4 v244, v[232:235], s[52:53] offset:832
	global_store_dwordx4 v244, v[236:239], s[52:53] offset:896
	global_store_dwordx4 v244, v[240:243], s[52:53] offset:960
	global_load_dwordx4 v[228:231], v245, s[52:53] offset:256
	global_load_dwordx4 v[232:235], v245, s[52:53] offset:320
	global_load_dwordx4 v[236:239], v245, s[52:53] offset:384
	global_load_dwordx4 v[240:243], v245, s[52:53] offset:448
	s_waitcnt vmcnt(4)
	v_fmac_f32_e32 v212, v148, v68
	v_fmac_f32_e32 v213, v149, v69
	v_fmac_f32_e32 v214, v150, v70
	v_fmac_f32_e32 v215, v151, v71
	v_fmac_f32_e32 v216, v152, v72
	v_fmac_f32_e32 v217, v153, v73
	v_fmac_f32_e32 v218, v154, v74
	v_fmac_f32_e32 v219, v155, v75
	v_fmac_f32_e32 v220, v156, v76
	v_fmac_f32_e32 v221, v157, v77
	v_fmac_f32_e32 v222, v158, v78
	v_fmac_f32_e32 v223, v159, v79
	v_fmac_f32_e32 v224, v160, v80
	v_fmac_f32_e32 v225, v161, v81
	v_fmac_f32_e32 v226, v162, v82
	v_fmac_f32_e32 v227, v163, v83
	global_store_dwordx4 v245, v[212:215], s[52:53]
	global_store_dwordx4 v245, v[216:219], s[52:53] offset:64
	global_store_dwordx4 v245, v[220:223], s[52:53] offset:128
	global_store_dwordx4 v245, v[224:227], s[52:53] offset:192
	global_load_dwordx4 v[212:215], v245, s[52:53] offset:512
	global_load_dwordx4 v[216:219], v245, s[52:53] offset:576
	global_load_dwordx4 v[220:223], v245, s[52:53] offset:640
	global_load_dwordx4 v[224:227], v245, s[52:53] offset:704
	s_waitcnt vmcnt(4)
	v_fmac_f32_e32 v228, v164, v84
	v_fmac_f32_e32 v229, v165, v85
	v_fmac_f32_e32 v230, v166, v86
	v_fmac_f32_e32 v231, v167, v87
	v_fmac_f32_e32 v232, v168, v88
	v_fmac_f32_e32 v233, v169, v89
	v_fmac_f32_e32 v234, v170, v90
	v_fmac_f32_e32 v235, v171, v91
	v_fmac_f32_e32 v236, v172, v92
	v_fmac_f32_e32 v237, v173, v93
	v_fmac_f32_e32 v238, v174, v94
	v_fmac_f32_e32 v239, v175, v95
	v_fmac_f32_e32 v240, v176, v96
	v_fmac_f32_e32 v241, v177, v97
	v_fmac_f32_e32 v242, v178, v98
	v_fmac_f32_e32 v243, v179, v99
	global_store_dwordx4 v245, v[228:231], s[52:53] offset:256
	global_store_dwordx4 v245, v[232:235], s[52:53] offset:320
	global_store_dwordx4 v245, v[236:239], s[52:53] offset:384
	global_store_dwordx4 v245, v[240:243], s[52:53] offset:448
	global_load_dwordx4 v[228:231], v245, s[52:53] offset:768
	global_load_dwordx4 v[232:235], v245, s[52:53] offset:832
	global_load_dwordx4 v[236:239], v245, s[52:53] offset:896
	global_load_dwordx4 v[240:243], v245, s[52:53] offset:960
	s_waitcnt vmcnt(4)
	v_fmac_f32_e32 v212, v180, v100
	v_fmac_f32_e32 v213, v181, v101
	v_fmac_f32_e32 v214, v182, v102
	v_fmac_f32_e32 v215, v183, v103
	v_fmac_f32_e32 v216, v184, v104
	v_fmac_f32_e32 v217, v185, v105
	v_fmac_f32_e32 v218, v186, v106
	v_fmac_f32_e32 v219, v187, v107
	v_fmac_f32_e32 v220, v188, v108
	v_fmac_f32_e32 v221, v189, v109
	v_fmac_f32_e32 v222, v190, v110
	v_fmac_f32_e32 v223, v191, v111
	v_fmac_f32_e32 v224, v192, v112
	v_fmac_f32_e32 v225, v193, v113
	v_fmac_f32_e32 v226, v194, v114
	v_fmac_f32_e32 v227, v195, v115
	global_store_dwordx4 v245, v[212:215], s[52:53] offset:512
	global_store_dwordx4 v245, v[216:219], s[52:53] offset:576
	global_store_dwordx4 v245, v[220:223], s[52:53] offset:640
	global_store_dwordx4 v245, v[224:227], s[52:53] offset:704
	s_waitcnt vmcnt(0)
	v_fmac_f32_e32 v228, v196, v116
	v_fmac_f32_e32 v229, v197, v117
	v_fmac_f32_e32 v230, v198, v118
	v_fmac_f32_e32 v231, v199, v119
	v_fmac_f32_e32 v232, v200, v120
	v_fmac_f32_e32 v233, v201, v121
	v_fmac_f32_e32 v234, v202, v122
	v_fmac_f32_e32 v235, v203, v123
	v_fmac_f32_e32 v236, v204, v124
	v_fmac_f32_e32 v237, v205, v125
	v_fmac_f32_e32 v238, v206, v126
	v_fmac_f32_e32 v239, v207, v127
	v_fmac_f32_e32 v240, v208, v128
	v_fmac_f32_e32 v241, v209, v129
	v_fmac_f32_e32 v242, v210, v130
	v_fmac_f32_e32 v243, v211, v131
	global_store_dwordx4 v245, v[228:231], s[52:53] offset:768
	global_store_dwordx4 v245, v[232:235], s[52:53] offset:832
	global_store_dwordx4 v245, v[236:239], s[52:53] offset:896
	global_store_dwordx4 v245, v[240:243], s[52:53] offset:960
